# gate/up: dropped the workgroup barrier + LDS wait after the row-scale (the table is only read in epilogues, after many K-loop barriers)
# speedup vs baseline: 1.0015x; 1.0013x over previous
.LBB0_1088:
	v_mbcnt_lo_u32_b32 v16, -1, 0
	v_mbcnt_hi_u32_b32 v16, -1, v16
	s_getreg_b32 s2, hwreg(HW_REG_HW_ID, 0, 6)
	s_lshl_b32 s2, s2, 2
	s_and_b32 s2, s2, 0xfc
	s_add_i32 s2, s2, 0
	s_add_i32 s2, s2, 0x23400
	v_mov_b32_e32 v0, s2
	ds_read_b32 v0, v0
	v_readlane_b32 s2, v255, 24
	s_or_b32 s45, s56, s2
	s_cmpk_gt_i32 s6, 0xaff
	s_waitcnt lgkmcnt(0)
	v_readfirstlane_b32 s2, v0
	s_nop 1
	v_lshl_add_u32 v0, s2, 6, v16
	s_nop 0
	v_readfirstlane_b32 s3, v0
	s_cbranch_scc1 .LBB0_1104
	v_lshlrev_b32_e32 v2, 4, v0
	v_add_u32_e32 v3, 0x2000, v2
	v_ashrrev_i32_e32 v4, 31, v3
	v_lshrrev_b32_e32 v4, 22, v4
	v_add_u32_e32 v4, v3, v4
	v_ashrrev_i32_e32 v10, 10, v4
	v_mul_i32_i24_e32 v4, 0x400, v10
	v_sub_u32_e32 v3, v3, v4
	v_lshrrev_b32_e32 v4, 4, v3
	v_bitop3_b32 v3, v4, v3, 32 bitop3:0x6c
	v_ashrrev_i32_e32 v4, 31, v3
	s_mul_i32 s4, s45, 0xb00000
	v_lshrrev_b32_e32 v4, 26, v4
	s_mul_hi_u32 s2, s45, 0xb00000
	s_add_u32 s4, s12, s4
	v_add_u32_e32 v4, v3, v4
	v_lshlrev_b32_e32 v5, 3, v10
	s_addc_u32 s2, s13, s2
	v_ashrrev_i32_e32 v11, 6, v4
	v_and_b32_e32 v5, -16, v5
	s_add_u32 s36, s4, 0x800000
	v_add_u32_e32 v5, v11, v5
	s_addc_u32 s37, s2, 0
	v_and_b32_e32 v6, 3, v11
	s_mov_b32 s2, 0x1fffe0
	v_lshrrev_b32_e32 v7, 2, v5
	v_lshlrev_b32_e32 v8, 1, v5
	v_and_b32_e32 v4, 0xc0, v4
	v_and_or_b32 v6, v5, s2, v6
	v_and_b32_e32 v7, 4, v7
	v_and_b32_e32 v8, 24, v8
	v_sub_u32_e32 v3, v3, v4
	v_or3_b32 v6, v6, v7, v8
	v_lshlrev_b32_e32 v7, 5, v10
	v_ashrrev_i16_sdwa v3, v226, sext(v3) dst_sel:DWORD dst_unused:UNUSED_PAD src0_sel:DWORD src1_sel:BYTE_0
	v_and_b32_e32 v7, 32, v7
	v_bfe_i32 v12, v3, 0, 16
	v_add_lshl_u32 v3, v7, v12, 1
	v_lshl_add_u32 v130, v6, 11, v3
	v_lshl_add_u32 v132, v5, 11, v3
	v_bfe_i32 v3, v0, 27, 1
	v_lshrrev_b32_e32 v3, 22, v3
	v_add_u32_e32 v3, v2, v3
	v_and_b32_e32 v3, 0xfffffc00, v3
	v_sub_u32_e32 v2, v2, v3
	v_lshrrev_b32_e32 v3, 4, v2
	v_ashrrev_i32_e32 v4, 31, v0
	v_bitop3_b32 v2, v3, v2, 32 bitop3:0x6c
	v_lshrrev_b32_e32 v4, 26, v4
	v_ashrrev_i32_e32 v3, 31, v2
	v_add_u32_e32 v0, v0, v4
	v_lshrrev_b32_e32 v3, 26, v3
	v_ashrrev_i32_e32 v14, 6, v0
	s_ashr_i32 s5, s3, 6
	v_add_u32_e32 v3, v2, v3
	v_lshlrev_b32_e32 v0, 3, v14
	s_ashr_i32 s14, s3, 8
	s_lshl_b32 s38, s5, 10
	v_ashrrev_i32_e32 v13, 6, v3
	v_and_b32_e32 v0, -16, v0
	s_add_u32 s39, s12, 0xdd00000
	v_add_u32_e32 v4, v13, v0
	v_and_b32_e32 v0, 3, v13
	s_addc_u32 s40, s13, 0
	v_and_or_b32 v0, v4, s2, v0
	s_ashr_i32 s2, s6, 31
	s_lshr_b32 s2, s2, 29
	s_add_i32 s2, s6, s2
	s_ashr_i32 s4, s2, 3
	s_and_b32 s2, s2, -8
	s_sub_i32 s2, s6, s2
	s_cmp_lt_i32 s2, 0
	s_cselect_b32 s8, s62, 0x160
	s_mul_i32 s2, s2, s8
	s_add_i32 s2, s2, s4
	s_mul_hi_i32 s4, s2, 0x2e8ba2e9
	s_lshr_b32 s8, s4, 31
	s_ashr_i32 s4, s4, 5
	s_add_i32 s4, s4, s8
	s_lshl_b32 s8, s4, 3
	s_mulk_i32 s4, 0xb0
	s_sub_i32 s2, s2, s4
	s_bfe_u32 s4, s2, 0x3001c
	s_add_i32 s9, s2, s4
	s_sext_i32_i16 s4, s9
	s_and_b32 s9, s9, 0xfff8
	s_sub_i32 s2, s2, s9
	s_sext_i32_i16 s2, s2
	v_lshrrev_b32_e32 v5, 2, v4
	v_lshlrev_b32_e32 v6, 1, v4
	v_and_b32_e32 v3, 0xc0, v3
	s_lshr_b32 s4, s4, 3
	s_add_i32 s24, s8, s2
	v_and_b32_e32 v5, 4, v5
	v_and_b32_e32 v6, 24, v6
	v_sub_u32_e32 v2, v2, v3
	s_ashr_i32 s25, s24, 31
	s_bfe_i64 s[16:17], s[4:5], 0x100000
	v_or3_b32 v0, v0, v5, v6
	v_lshlrev_b32_e32 v5, 5, v14
	v_ashrrev_i16_sdwa v2, v226, sext(v2) dst_sel:DWORD dst_unused:UNUSED_PAD src0_sel:DWORD src1_sel:BYTE_0
	s_lshl_b64 s[8:9], s[24:25], 19
	s_lshl_b64 s[16:17], s[16:17], 19
	v_and_b32_e32 v5, 32, v5
	v_bfe_i32 v15, v2, 0, 16
	s_add_u32 s28, s36, s16
	v_add_lshl_u32 v2, v5, v15, 1
	s_addc_u32 s29, s37, s17
	s_add_i32 s41, s38, 0
	v_lshl_add_u32 v0, v0, 11, v2
	s_add_i32 m0, s41, 0x10000
	v_lshl_add_u32 v134, v4, 11, v2
	global_load_lds_dwordx4 v0, s[28:29]
	s_add_i32 m0, s41, 0x12000
	s_add_u32 s16, s28, 0x40000
	global_load_lds_dwordx4 v130, s[28:29]
	s_addc_u32 s17, s29, 0
	s_add_i32 m0, s41, 0x14000
	v_mov_b32_e32 v131, v1
	global_load_lds_dwordx4 v0, s[16:17]
	s_add_i32 m0, s41, 0x16000
	s_add_u32 s26, s39, s8
	s_addc_u32 s27, s40, s9
	s_add_i32 s42, s41, 0x2000
	global_load_lds_dwordx4 v130, s[16:17]
	s_mov_b32 m0, s41
	s_add_u32 s8, s26, 0x40000
	global_load_lds_dwordx4 v134, s[26:27]
	s_mov_b32 m0, s42
	s_addc_u32 s9, s27, 0
	s_add_i32 s43, s41, 0x4000
	global_load_lds_dwordx4 v132, s[26:27]
	s_mov_b32 m0, s43
	s_add_i32 s46, s41, 0x6000
	global_load_lds_dwordx4 v134, s[8:9]
	s_mov_b32 m0, s46
	v_mov_b32_e32 v135, v1
	global_load_lds_dwordx4 v132, s[8:9]
	v_mov_b32_e32 v133, v1
	s_cmp_eq_u32 s14, 1
	v_lshl_add_u64 v[8:9], s[28:29], 0, v[0:1]
	v_lshl_add_u64 v[6:7], s[28:29], 0, v[130:131]
	v_lshl_add_u64 v[2:3], s[26:27], 0, v[134:135]
	s_cselect_b64 s[8:9], -1, 0
	s_cmp_lg_u32 s14, 1
	v_lshl_add_u64 v[4:5], s[26:27], 0, v[132:133]
	s_cbranch_scc1 .LBB0_1091
	s_barrier
